# RG-LRU local scan: loop-top counted waits for the prefetched rows raised by 32 so they no longer wait for the 32 younger scan stores (in-order vmcnt); one full wait before the first sub-batch
# speedup vs baseline: 1.0052x; 1.0052x over previous
; DEV float bf2f(unsigned short h) { return __uint_as_float(((unsigned)h) << 16); }
; __device__ void lru_local_item(const Params& P, int l, int item, char* smem) {
;     ...
;   const float lam = P.lru_lambda[l * 512 + ch];
;   const float z = -lam;
;   const float sp = fmaxf(z, 0.f) + log1pf(__expf(-fabsf(z)));
;   const float nl = -8.0f * sp;
;   const int s0 = j * 64;
;   const bf16_t* hx = P.H + (size_t)(b * SEQ) * HS + ch;
;   float xm3 = (s0 - 3 >= 0) ? bf2f(hx[(size_t)(s0 - 3) * HS]) : 0.f;
;   float xm2 = (s0 - 2 >= 0) ? bf2f(hx[(size_t)(s0 - 2) * HS]) : 0.f;
;   float xm1 = (s0 - 1 >= 0) ? bf2f(hx[(size_t)(s0 - 1) * HS]) : 0.f;
;   float h = 0.f, pc = 1.f;
;   unsigned short hv[16], hn[16];
; #pragma unroll
;   for (int i = 0; i < 16; ++i) { hv[i] = hx[(size_t)(s0 + i) * HS]; hn[i] = hv[i]; }
.LBB0_294:
	s_mov_b32 s0, 0xbfb8aa3b
	s_waitcnt vmcnt(0)
	v_mul_f32_e64 v71, |v70|, s0
	v_exp_f32_e32 v114, v71
	v_max_f32_e64 v70, -v70, -v70
	v_max_f32_e32 v115, 0, v70
	s_mov_b32 s0, 0x3f2aaaab
	v_add_f32_e32 v74, 1.0, v114
	v_add_f32_e32 v70, -1.0, v74
	v_sub_f32_e32 v71, v70, v74
	v_add_f32_e32 v71, 1.0, v71
	v_sub_f32_e32 v70, v114, v70
	v_add_f32_e32 v75, v70, v71
	v_frexp_mant_f32_e32 v76, v74
	v_cvt_f64_f32_e32 v[70:71], v74
	v_frexp_exp_i32_f64_e32 v70, v[70:71]
	v_cmp_gt_f32_e32 vcc, s0, v76
	s_mul_i32 s0, s40, 0x40c00
	s_mov_b32 s1, s3
	v_subbrev_co_u32_e32 v116, vcc, 0, v70, vcc
	v_sub_u32_e32 v70, 0, v116
	v_ldexp_f32 v71, v74, v70
	v_add_f32_e32 v74, -1.0, v71
	v_add_f32_e32 v77, 1.0, v71
	v_ldexp_f32 v70, v75, v70
	v_add_f32_e32 v75, 1.0, v74
	v_add_f32_e32 v90, -1.0, v77
	v_sub_f32_e32 v75, v71, v75
	v_sub_f32_e32 v71, v71, v90
	v_add_f32_e32 v75, v70, v75
	v_add_f32_e32 v70, v70, v71
	v_add_f32_e32 v71, v77, v70
	v_rcp_f32_e32 v90, v71
	v_add_f32_e32 v76, v74, v75
	v_sub_f32_e32 v74, v76, v74
	v_sub_f32_e32 v74, v75, v74
	v_sub_f32_e32 v75, v71, v77
	v_sub_f32_e32 v70, v70, v75
	v_mul_f32_e32 v75, v76, v90
	v_mul_f32_e32 v77, v71, v75
	v_fma_f32 v91, v75, v71, -v77
	v_fmac_f32_e32 v91, v75, v70
	v_add_f32_e32 v92, v77, v91
	v_sub_f32_e32 v93, v76, v92
	v_sub_f32_e32 v76, v76, v93
	v_sub_f32_e32 v77, v92, v77
	v_sub_f32_e32 v76, v76, v92
	v_add_f32_e32 v74, v74, v76
	v_sub_f32_e32 v76, v77, v91
	v_add_f32_e32 v74, v76, v74
	v_add_f32_e32 v76, v93, v74
	v_mul_f32_e32 v77, v90, v76
	v_mul_f32_e32 v91, v71, v77
	v_fma_f32 v71, v77, v71, -v91
	v_fmac_f32_e32 v71, v77, v70
	v_sub_f32_e32 v70, v93, v76
	v_add_f32_e32 v70, v74, v70
	v_add_f32_e32 v74, v91, v71
	v_sub_f32_e32 v92, v76, v74
	v_sub_f32_e32 v76, v76, v92
	v_sub_f32_e32 v91, v74, v91
	v_sub_f32_e32 v74, v76, v74
	v_add_f32_e32 v70, v70, v74
	v_sub_f32_e32 v71, v91, v71
	v_add_f32_e32 v70, v71, v70
	v_add_f32_e32 v117, v75, v77
	v_add_f32_e32 v70, v92, v70
	v_sub_f32_e32 v71, v117, v75
	v_mul_f32_e32 v70, v90, v70
	v_sub_f32_e32 v71, v77, v71
	v_add_f32_e32 v118, v71, v70
	v_lshl_add_u64 v[70:71], v[66:67], 0, s[0:1]
	s_movk_i32 s0, 0x1000
	v_add_co_u32_e32 v74, vcc, s0, v70
	s_movk_i32 s0, 0x3000
	s_nop 0
	v_addc_co_u32_e32 v75, vcc, 0, v71, vcc
	v_add_co_u32_e32 v76, vcc, s65, v70
	v_add_f32_e32 v119, v117, v118
	s_nop 0
	v_addc_co_u32_e32 v77, vcc, 0, v71, vcc
	v_add_co_u32_e32 v90, vcc, s0, v70
	s_movk_i32 s0, 0x5000
	s_nop 0
	v_addc_co_u32_e32 v91, vcc, 0, v71, vcc
	v_add_co_u32_e32 v92, vcc, s97, v70
	s_lshl_b32 s1, s37, 14
	s_nop 0
	v_addc_co_u32_e32 v93, vcc, 0, v71, vcc
	v_add_co_u32_e32 v94, vcc, s0, v70
	s_movk_i32 s0, 0x6000
	s_nop 0
	v_addc_co_u32_e32 v95, vcc, 0, v71, vcc
	v_add_co_u32_e32 v104, vcc, s0, v70
	s_movk_i32 s0, 0x7000
	s_nop 0
	v_addc_co_u32_e32 v105, vcc, 0, v71, vcc
	v_add_co_u32_e32 v106, vcc, s0, v70
	s_mov_b32 s0, 0x8000
	s_nop 0
	v_addc_co_u32_e32 v107, vcc, 0, v71, vcc
	global_load_ushort v103, v[70:71], off
	global_load_ushort v101, v[74:75], off offset:48
	global_load_ushort v100, v[76:77], off offset:96
	global_load_ushort v99, v[90:91], off offset:144
	global_load_ushort v98, v[92:93], off offset:192
	global_load_ushort v97, v[94:95], off offset:240
	global_load_ushort v96, v[104:105], off offset:288
	global_load_ushort v102, v[106:107], off offset:336
	v_add_co_u32_e32 v74, vcc, s0, v70
	s_mov_b32 s0, 0x9000
	s_nop 0
	v_addc_co_u32_e32 v75, vcc, 0, v71, vcc
	v_add_co_u32_e32 v76, vcc, s0, v70
	s_mov_b32 s0, 0xa000
	s_nop 0
	v_addc_co_u32_e32 v77, vcc, 0, v71, vcc
	v_add_co_u32_e32 v90, vcc, s0, v70
	s_mov_b32 s0, 0xb000
	s_nop 0
	v_addc_co_u32_e32 v91, vcc, 0, v71, vcc
	v_add_co_u32_e32 v92, vcc, s0, v70
	s_mov_b32 s0, 0xc000
	s_nop 0
	v_addc_co_u32_e32 v93, vcc, 0, v71, vcc
	v_add_co_u32_e32 v94, vcc, s0, v70
	s_mov_b32 s0, 0xd000
	s_nop 0
	v_addc_co_u32_e32 v95, vcc, 0, v71, vcc
	v_add_co_u32_e32 v104, vcc, s0, v70
	s_mov_b32 s0, 0xe000
	s_nop 0
	v_addc_co_u32_e32 v105, vcc, 0, v71, vcc
	v_add_co_u32_e32 v112, vcc, s0, v70
	s_mov_b32 s0, 0xf000
	s_nop 0
	v_addc_co_u32_e32 v113, vcc, 0, v71, vcc
	v_add_co_u32_e32 v70, vcc, s0, v70
	s_mov_b32 s0, 0x3f317218
	s_nop 0
	v_addc_co_u32_e32 v71, vcc, 0, v71, vcc
	global_load_ushort v111, v[74:75], off offset:384
	global_load_ushort v109, v[76:77], off offset:432
	global_load_ushort v108, v[90:91], off offset:480
	global_load_ushort v107, v[92:93], off offset:528
	global_load_ushort v106, v[94:95], off offset:576
	s_nop 0
	global_load_ushort v105, v[104:105], off offset:624
	s_nop 0
	global_load_ushort v104, v[112:113], off offset:672
	global_load_ushort v110, v[70:71], off offset:720
	v_cvt_f32_i32_e32 v70, v116
	v_mul_f32_e32 v71, v119, v119
	v_fmamk_f32 v74, v71, 0x3e9b6dac, v205
	v_fmaak_f32 v74, v71, v74, 0x3f2aaada
	v_mul_f32_e32 v75, 0x3f317218, v70
	v_fma_f32 v76, v70, s0, -v75
	v_fmac_f32_e32 v76, 0xb102e308, v70
	v_add_f32_e32 v77, v75, v76
	v_sub_f32_e32 v75, v77, v75
	v_mul_f32_e32 v71, v119, v71
	v_sub_f32_e32 v75, v76, v75
	v_ldexp_f32 v76, v119, 1
	v_mul_f32_e32 v71, v71, v74
	v_sub_f32_e32 v70, v119, v117
	v_add_f32_e32 v74, v76, v71
	v_sub_f32_e32 v70, v118, v70
	v_sub_f32_e32 v76, v74, v76
	v_ldexp_f32 v70, v70, 1
	v_sub_f32_e32 v71, v71, v76
	v_add_f32_e32 v70, v70, v71
	v_add_f32_e32 v71, v74, v70
	v_sub_f32_e32 v74, v71, v74
	v_sub_f32_e32 v70, v70, v74
	v_add_f32_e32 v74, v77, v71
	v_sub_f32_e32 v76, v74, v77
	v_sub_f32_e32 v90, v74, v76
	v_sub_f32_e32 v77, v77, v90
	v_sub_f32_e32 v71, v71, v76
	v_add_f32_e32 v76, v75, v70
	v_add_f32_e32 v71, v71, v77
	v_sub_f32_e32 v77, v76, v75
	v_sub_f32_e32 v90, v76, v77
	v_sub_f32_e32 v75, v75, v90
	v_sub_f32_e32 v70, v70, v77
; DEV unsigned short f2bf(float f) { return (unsigned short)(pack2(f, 0.f) & 0xFFFFu); }
; DEV float bf2f(unsigned short h) { return __uint_as_float(((unsigned)h) << 16); }
; __device__ void lru_local_item(const Params& P, int l, int item, char* smem) {
;     ...
;   const float sp = fmaxf(z, 0.f) + log1pf(__expf(-fabsf(z)));
;   const float nl = -8.0f * sp;
;   const int s0 = j * 64;
;   const bf16_t* hx = P.H + (size_t)(b * SEQ) * HS + ch;
;   float xm3 = (s0 - 3 >= 0) ? bf2f(hx[(size_t)(s0 - 3) * HS]) : 0.f;
;   float xm2 = (s0 - 2 >= 0) ? bf2f(hx[(size_t)(s0 - 2) * HS]) : 0.f;
;   float xm1 = (s0 - 1 >= 0) ? bf2f(hx[(size_t)(s0 - 1) * HS]) : 0.f;
;   float h = 0.f, pc = 1.f;
;   unsigned short hv[16], hn[16];
; #pragma unroll
;   for (int i = 0; i < 16; ++i) { hv[i] = hx[(size_t)(s0 + i) * HS]; hn[i] = hv[i]; }
; #pragma unroll 1
;   for (int sub = 0; sub < 4; ++sub) {
;     __syncthreads();
; #pragma unroll
;     for (int i = 0; i < 16; ++i) {
;       const float xv = bf2f(hv[i]);
;       const float xc = cb + cw0 * xm3 + cw1 * xm2 + cw2 * xm1 + cw3 * xv;
;       xm3 = xm2; xm2 = xm1; xm1 = xv;
;       xs[i * 256 + tid] = xc;
;       xb[i * 264 + tid] = f2bf(xc);
;     }
;     __syncthreads();
	v_add_f32_e32 v71, v76, v71
	v_add_f32_e32 v70, v70, v75
	v_add_f32_e32 v75, v74, v71
	v_sub_f32_e32 v74, v75, v74
	v_sub_f32_e32 v71, v71, v74
	v_add_f32_e32 v70, v70, v71
	s_mov_b32 s0, 0x7f800000
	v_add_f32_e32 v70, v75, v70
	v_cmp_neq_f32_e32 vcc, s0, v114
	s_mov_b32 s0, 0x33800000
	s_and_b32 s1, s1, 0x1f8000
	v_cndmask_b32_e32 v70, v222, v70, vcc
	v_cmp_ngt_f32_e32 vcc, -1.0, v114
	v_bfe_u32 v79, v68, 4, 2
	v_lshlrev_b32_e32 v71, 7, v68
	v_cndmask_b32_e32 v70, v223, v70, vcc
	v_cmp_neq_f32_e32 vcc, -1.0, v114
	v_and_b32_e32 v73, 63, v68
	v_and_b32_e32 v71, 0xffffe000, v71
	v_cndmask_b32_e32 v70, v224, v70, vcc
	v_cmp_lt_f32_e64 vcc, |v114|, s0
	s_lshl_b32 s0, s33, 14
	s_and_b32 s0, s0, 0xffe00000
	v_cndmask_b32_e32 v70, v70, v114, vcc
	v_add_f32_e32 v70, v115, v70
	v_mul_f32_e32 v90, 0xc1000000, v70
	v_lshlrev_b32_e32 v70, 1, v68
	v_sub_u32_e32 v74, 0, v70
	v_and_b32_e32 v70, 0x7fffffc0, v68
	s_or_b32 s2, s0, s1
	v_lshlrev_b32_e32 v70, 1, v70
	s_movk_i32 s1, 0x210
	s_and_b32 s0, s7, 0x100
	v_mad_u32_u24 v75, v69, s1, v70
	v_lshlrev_b32_e32 v70, 10, v79
	v_lshlrev_b32_e32 v69, 2, v69
	v_lshlrev_b32_e32 v91, 2, v68
	v_or3_b32 v92, v71, v70, v69
	v_lshl_or_b32 v69, v73, 2, v71
	v_add_u32_e32 v68, s0, v68
	v_add_u32_e32 v93, 0x6200, v69
	v_ashrrev_i32_e32 v69, 31, v68
	v_lshl_add_u64 v[68:69], v[68:69], 0, s[2:3]
	v_lshlrev_b64 v[70:71], 1, v[68:69]
	v_mov_b32_e32 v78, 1.0
	s_mov_b32 s38, 0
	v_lshl_add_u64 v[68:69], s[60:61], 0, v[70:71]
	v_lshl_add_u64 v[70:71], s[62:63], 0, v[70:71]
	v_add_u32_e32 v94, v91, v74
	v_add_u32_e32 v95, v75, v176
	s_mov_b32 s39, s2
	s_waitcnt vmcnt(0)
.LBB0_295:
	v_fma_f32 v74, v80, v88, v84
	v_fmac_f32_e32 v74, v81, v87
	s_waitcnt vmcnt(47)
	v_lshlrev_b32_e32 v73, 16, v103
	v_fmac_f32_e32 v74, v82, v89
	v_fmac_f32_e32 v74, v83, v73
	v_fma_f32 v76, v80, v87, v84
	v_cvt_pk_bf16_f32 v75, v74, s0
	v_fmac_f32_e32 v76, v81, v89
	s_barrier
	ds_write_b16 v94, v75 offset:16384
	s_waitcnt vmcnt(46)
	v_lshlrev_b32_e32 v75, 16, v101
	v_fmac_f32_e32 v76, v82, v73
	v_fmac_f32_e32 v76, v83, v75
	ds_write2st64_b32 v91, v74, v76 offset1:4
	v_cvt_pk_bf16_f32 v74, v76, s0
	v_fma_f32 v76, v80, v89, v84
	v_fmac_f32_e32 v76, v81, v73
	ds_write_b16 v94, v74 offset:16912
	s_waitcnt vmcnt(45)
	v_lshlrev_b32_e32 v74, 16, v100
	v_fmac_f32_e32 v76, v82, v75
	v_fmac_f32_e32 v76, v83, v74
	v_fma_f32 v73, v80, v73, v84
	v_cvt_pk_bf16_f32 v77, v76, s0
	v_fmac_f32_e32 v73, v81, v75
	ds_write_b16 v94, v77 offset:17440
	s_waitcnt vmcnt(44)
	v_lshlrev_b32_e32 v77, 16, v99
	v_fmac_f32_e32 v73, v82, v74
	v_fmac_f32_e32 v73, v83, v77
	v_fma_f32 v75, v80, v75, v84
	ds_write2st64_b32 v91, v76, v73 offset0:8 offset1:12
	v_cvt_pk_bf16_f32 v73, v73, s0
	v_fmac_f32_e32 v75, v81, v74
	ds_write_b16 v94, v73 offset:17968
	s_waitcnt vmcnt(43)
	v_lshlrev_b32_e32 v73, 16, v98
	v_fmac_f32_e32 v75, v82, v77
	v_fmac_f32_e32 v75, v83, v73
	v_fma_f32 v74, v80, v74, v84
	v_cvt_pk_bf16_f32 v76, v75, s0
	v_fmac_f32_e32 v74, v81, v77
	ds_write_b16 v94, v76 offset:18496
	s_waitcnt vmcnt(42)
	v_lshlrev_b32_e32 v76, 16, v97
	v_fmac_f32_e32 v74, v82, v73
	v_fmac_f32_e32 v74, v83, v76
	ds_write2st64_b32 v91, v75, v74 offset0:16 offset1:20
	v_fma_f32 v75, v80, v77, v84
	v_cvt_pk_bf16_f32 v74, v74, s0
	v_fmac_f32_e32 v75, v81, v73
	ds_write_b16 v94, v74 offset:19024
	s_waitcnt vmcnt(41)
	v_lshlrev_b32_e32 v74, 16, v96
	v_fmac_f32_e32 v75, v82, v76
	v_fmac_f32_e32 v75, v83, v74
	v_fma_f32 v73, v80, v73, v84
	v_cvt_pk_bf16_f32 v77, v75, s0
	v_fmac_f32_e32 v73, v81, v76
	ds_write_b16 v94, v77 offset:19552
	s_waitcnt vmcnt(40)
	v_lshlrev_b32_e32 v77, 16, v102
	v_fmac_f32_e32 v73, v82, v74
	v_fmac_f32_e32 v73, v83, v77
	ds_write2st64_b32 v91, v75, v73 offset0:24 offset1:28
	v_fma_f32 v75, v80, v76, v84
	v_cvt_pk_bf16_f32 v73, v73, s0
	v_fmac_f32_e32 v75, v81, v74
	ds_write_b16 v94, v73 offset:20080
	s_waitcnt vmcnt(39)
	v_lshlrev_b32_e32 v73, 16, v111
	v_fmac_f32_e32 v75, v82, v77
	v_fmac_f32_e32 v75, v83, v73
	v_fma_f32 v74, v80, v74, v84
	v_cvt_pk_bf16_f32 v76, v75, s0
	v_fmac_f32_e32 v74, v81, v77
	ds_write_b16 v94, v76 offset:20608
	s_waitcnt vmcnt(38)
	v_lshlrev_b32_e32 v76, 16, v109
	v_fmac_f32_e32 v74, v82, v73
	v_fmac_f32_e32 v74, v83, v76
	ds_write2st64_b32 v91, v75, v74 offset0:32 offset1:36
	v_fma_f32 v75, v80, v77, v84
	v_cvt_pk_bf16_f32 v74, v74, s0
	v_fmac_f32_e32 v75, v81, v73
	ds_write_b16 v94, v74 offset:21136
	s_waitcnt vmcnt(37)
	v_lshlrev_b32_e32 v74, 16, v108
	v_fmac_f32_e32 v75, v82, v76
	v_fmac_f32_e32 v75, v83, v74
	v_fma_f32 v73, v80, v73, v84
	v_cvt_pk_bf16_f32 v77, v75, s0
	v_fmac_f32_e32 v73, v81, v76
	ds_write_b16 v94, v77 offset:21664
	s_waitcnt vmcnt(36)
	v_lshlrev_b32_e32 v77, 16, v107
	v_fmac_f32_e32 v73, v82, v74
	v_fmac_f32_e32 v73, v83, v77
	ds_write2st64_b32 v91, v75, v73 offset0:40 offset1:44
	v_fma_f32 v75, v80, v76, v84
	v_cvt_pk_bf16_f32 v73, v73, s0
	v_fmac_f32_e32 v75, v81, v74
	v_fma_f32 v74, v80, v74, v84
	ds_write_b16 v94, v73 offset:22192
	s_waitcnt vmcnt(35)
	v_lshlrev_b32_e32 v73, 16, v106
	v_fmac_f32_e32 v74, v81, v77
	v_fmac_f32_e32 v75, v82, v77
	s_waitcnt vmcnt(34)
	v_lshlrev_b32_e32 v88, 16, v105
	v_fmac_f32_e32 v74, v82, v73
	v_fmac_f32_e32 v75, v83, v73
	v_fmac_f32_e32 v74, v83, v88
	ds_write2st64_b32 v91, v75, v74 offset0:48 offset1:52
	v_cvt_pk_bf16_f32 v74, v74, s0
	ds_write_b16 v94, v74 offset:23248
	v_fma_f32 v74, v80, v77, v84
	v_fmac_f32_e32 v74, v81, v73
	v_fma_f32 v73, v80, v73, v84
	s_waitcnt vmcnt(33)
	v_lshlrev_b32_e32 v87, 16, v104
	v_fmac_f32_e32 v73, v81, v88
	v_fmac_f32_e32 v74, v82, v88
	s_waitcnt vmcnt(32)
	v_lshlrev_b32_e32 v89, 16, v110
	v_fmac_f32_e32 v73, v82, v87
	v_fmac_f32_e32 v74, v83, v87
	v_fmac_f32_e32 v73, v83, v89
	v_cvt_pk_bf16_f32 v76, v75, s0
	v_cvt_pk_bf16_f32 v75, v74, s0
	ds_write2st64_b32 v91, v74, v73 offset0:56 offset1:60
	v_cvt_pk_bf16_f32 v73, v73, s0
	ds_write_b16 v94, v76 offset:22720
	ds_write_b16 v94, v75 offset:23776
	ds_write_b16 v94, v73 offset:24304
	s_waitcnt lgkmcnt(0)
	s_barrier
; DEV f32x4 mfma16(bf16x8 a, bf16x8 b, f32x4 c) { return __builtin_amdgcn_mfma_f32_16x16x32_bf16(a, b, c, 0, 0, 0); }
; __device__ void lru_local_item(const Params& P, int l, int item, char* smem) {
;     ...
;     {
;       bf16x8 af[2];
; #pragma unroll
;       for (int ks = 0; ks < 2; ++ks) af[ks] = *(const bf16x8*)(xb + r16 * 264 + w * 64 + ks * 32 + kq * 8);
; #pragma unroll
;       for (int mat = 0; mat < 2; ++mat)
; #pragma unroll
;         for (int nt = 0; nt < 4; ++nt) {
;           f32x4 acc = {0.f, 0.f, 0.f, 0.f};
;           acc = mfma16(af[0], bw[mat][nt][0], acc);
;           acc = mfma16(af[1], bw[mat][nt][1], acc);
; #pragma unroll
;           for (int r = 0; r < 4; ++r) cs[mat * 1024 + (kq * 4 + r) * 64 + nt * 16 + r16] = acc[r];
;         }
;     }
;     {
;       const int sn = s0 + ((sub < 3) ? (sub + 1) * 16 : sub * 16);
; #pragma unroll
;       for (int i = 0; i < 16; ++i) hn[i] = hx[(size_t)(sn + i) * HS];
;     }
;     __syncthreads();
	ds_read_b128 v[74:77], v95 offset:16384
	ds_read_b128 v[96:99], v95 offset:16448
	s_waitcnt lgkmcnt(1)
	v_mfma_f32_16x16x32_bf16 v[100:103], v[74:77], v[0:3], 0
	v_add_u32_e32 v73, 0x6000, v92
	v_add_u32_e32 v79, 0x6400, v92
	s_lshl_b32 s0, s38, 4
	v_mfma_f32_16x16x32_bf16 v[104:107], v[74:77], v[8:11], 0
	s_add_i32 s0, s0, 16
	s_cmp_lg_u32 s38, 3
	s_cselect_b32 s0, s0, 48
	s_waitcnt lgkmcnt(0)
	v_mfma_f32_16x16x32_bf16 v[100:103], v[96:99], v[4:7], v[100:103]
	s_add_i32 s0, s0, s42
	s_mul_i32 s2, s0, 0x818
	s_add_i32 s0, s2, 0x818
	v_mfma_f32_16x16x32_bf16 v[104:107], v[96:99], v[12:15], v[104:107]
	s_nop 7
	ds_write2_b32 v73, v100, v104 offset0:128 offset1:144
	ds_write2_b32 v73, v101, v105 offset0:192 offset1:208
	ds_write2_b32 v79, v102, v106 offset1:16
	ds_write2_b32 v79, v103, v107 offset0:64 offset1:80
	v_mfma_f32_16x16x32_bf16 v[100:103], v[74:77], v[16:19], 0
	s_mov_b32 s1, s3
	s_mov_b32 s43, 0
	v_mov_b32_e32 v112, v91
	v_mfma_f32_16x16x32_bf16 v[104:107], v[74:77], v[24:27], 0
	v_mov_b32_e32 v113, v93
	s_mov_b32 s45, 0xf800000
	v_mfma_f32_16x16x32_bf16 v[100:103], v[96:99], v[20:23], v[100:103]
	v_mfma_f32_16x16x32_bf16 v[104:107], v[96:99], v[28:31], v[104:107]
	s_nop 7
	ds_write2_b32 v73, v100, v104 offset0:160 offset1:176
	ds_write2_b32 v73, v101, v105 offset0:224 offset1:240
	ds_write2_b32 v79, v102, v106 offset0:32 offset1:48
	ds_write2_b32 v79, v103, v107 offset0:96 offset1:112
	v_mfma_f32_16x16x32_bf16 v[100:103], v[74:77], v[32:35], 0
	v_add_u32_e32 v73, 0x7000, v92
	v_add_u32_e32 v79, 0x7400, v92
	v_mfma_f32_16x16x32_bf16 v[104:107], v[74:77], v[40:43], 0
	v_mfma_f32_16x16x32_bf16 v[100:103], v[96:99], v[36:39], v[100:103]
	v_mfma_f32_16x16x32_bf16 v[104:107], v[96:99], v[44:47], v[104:107]
	s_nop 7
	ds_write2_b32 v73, v100, v104 offset0:128 offset1:144
	ds_write2_b32 v73, v101, v105 offset0:192 offset1:208
	ds_write2_b32 v79, v102, v106 offset1:16
	ds_write2_b32 v79, v103, v107 offset0:64 offset1:80
	v_mfma_f32_16x16x32_bf16 v[100:103], v[74:77], v[48:51], 0
	v_mfma_f32_16x16x32_bf16 v[74:77], v[74:77], v[56:59], 0
	v_mfma_f32_16x16x32_bf16 v[100:103], v[96:99], v[52:55], v[100:103]
	v_mfma_f32_16x16x32_bf16 v[74:77], v[96:99], v[60:63], v[74:77]
	s_nop 7
	ds_write2_b32 v73, v100, v74 offset0:160 offset1:176
	ds_write2_b32 v73, v101, v75 offset0:224 offset1:240
	ds_write2_b32 v79, v102, v76 offset0:32 offset1:48
	ds_write2_b32 v79, v103, v77 offset0:96 offset1:112
	v_lshl_add_u64 v[74:75], s[2:3], 1, v[66:67]
	global_load_ushort v103, v[74:75], off
	v_lshl_add_u64 v[74:75], s[0:1], 1, v[66:67]
	s_add_i32 s0, s2, 0x1030
	global_load_ushort v101, v[74:75], off
	v_lshl_add_u64 v[74:75], s[0:1], 1, v[66:67]
	s_add_i32 s0, s2, 0x1848
	global_load_ushort v100, v[74:75], off
	v_lshl_add_u64 v[74:75], s[0:1], 1, v[66:67]
	s_add_i32 s0, s2, 0x2060
	global_load_ushort v99, v[74:75], off
	v_lshl_add_u64 v[74:75], s[0:1], 1, v[66:67]
	s_add_i32 s0, s2, 0x2878
	global_load_ushort v98, v[74:75], off
	v_lshl_add_u64 v[74:75], s[0:1], 1, v[66:67]
	s_add_i32 s0, s2, 0x3090
	global_load_ushort v97, v[74:75], off
	v_lshl_add_u64 v[74:75], s[0:1], 1, v[66:67]
	s_add_i32 s0, s2, 0x38a8
	global_load_ushort v96, v[74:75], off
	v_lshl_add_u64 v[74:75], s[0:1], 1, v[66:67]
	s_add_i32 s0, s2, 0x40c0
	global_load_ushort v102, v[74:75], off
	v_lshl_add_u64 v[74:75], s[0:1], 1, v[66:67]
	s_add_i32 s0, s2, 0x48d8
	global_load_ushort v111, v[74:75], off
	v_lshl_add_u64 v[74:75], s[0:1], 1, v[66:67]
	s_add_i32 s0, s2, 0x50f0
	global_load_ushort v109, v[74:75], off
	v_lshl_add_u64 v[74:75], s[0:1], 1, v[66:67]
	s_add_i32 s0, s2, 0x5908
	global_load_ushort v108, v[74:75], off
	v_lshl_add_u64 v[74:75], s[0:1], 1, v[66:67]
	s_add_i32 s0, s2, 0x6120
	global_load_ushort v107, v[74:75], off
	v_lshl_add_u64 v[74:75], s[0:1], 1, v[66:67]
	s_add_i32 s0, s2, 0x6938
	global_load_ushort v106, v[74:75], off
	v_lshl_add_u64 v[74:75], s[0:1], 1, v[66:67]
	s_add_i32 s0, s2, 0x7150
	global_load_ushort v105, v[74:75], off
	v_lshl_add_u64 v[74:75], s[0:1], 1, v[66:67]
	s_addk_i32 s2, 0x7968
	global_load_ushort v104, v[74:75], off
	v_lshl_add_u64 v[74:75], s[2:3], 1, v[66:67]
	global_load_ushort v110, v[74:75], off
	v_mov_b64_e32 v[74:75], v[70:71]
	v_mov_b64_e32 v[76:77], v[68:69]
	s_waitcnt lgkmcnt(0)
	s_barrier
